# EpiScale epilogue: bf16 tile stores flat_store -> global_store (no lgkmcnt coupling with the row-scale LDS reads)
# baseline (speedup 1.0000x reference)
; #define LAS __attribute__((address_space(3)))
;     __device__ __forceinline__ void operator()(const f32x4 (&acc)[2][2][4][2], const Unit& u, const LAS float* rsl, int wr, int wc, int fr, int fq) const {
; #pragma unroll
;         for (int ai = 0; ai < 2; ++ai)
; #pragma unroll
;             for (int m = 0; m < 4; ++m) {
;                 const int rl = ai * HALF + wr * 64 + m * 16 + fr, row = u.pm * BM + rl;
;                 const float rs = rsl[rl] * cs;
; #pragma unroll
;                 for (int bj = 0; bj < 2; ++bj) {
;                     const int col = u.pn * BM + bj * HALF + wc * 32 + 8 * fq;
;                     const f32x4 v0 = acc[ai][bj][m][0] * rs, v1 = acc[ai][bj][m][1] * rs;
;                     if (mode == 0) {
;                         *(bf16x8*)(O + (size_t)row * ldc + col) = pack8v(v0, v1);
;                     } else {
;                         const int t = col >> 10, c = col & 1023;
;                         *(bf16x8*)(O + ((size_t)t * 512 + row) * 1024 + c) = pack8v(v0, v1);
;                         float* o = out32 + (size_t)(t & 1) * (OFF_MV - OFF_MK) + (size_t)(t >> 1) * (512 * 1024) + (size_t)row * 1024 + c;
;                         *(f32x4*)o = v0; *(f32x4*)(o + 4) = v1;
;                     }
;                 }
;             }
;     }
.LBB0_504:
	s_lshl_b32 s6, s7, 10
	v_add_u32_e32 v178, s6, v176
	ds_read_b32 v0, v178
	s_lshl_b32 s51, s38, 8
	v_add_u32_e32 v154, s51, v166
	v_lshl_or_b32 v150, s36, 8, v175
	v_ashrrev_i32_e32 v155, 31, v154
	s_waitcnt lgkmcnt(0)
	v_mul_f32_e32 v156, s17, v0
	v_pk_mul_f32 v[132:133], v[96:97], v[156:157] op_sel_hi:[1,0]
	v_pk_mul_f32 v[130:131], v[94:95], v[156:157] op_sel_hi:[1,0]
	v_pk_mul_f32 v[136:137], v[92:93], v[156:157] op_sel_hi:[1,0]
	v_pk_mul_f32 v[134:135], v[90:91], v[156:157] op_sel_hi:[1,0]
	s_mov_b64 s[68:69], -1
	s_andn2_b64 vcc, exec, s[26:27]
	v_ashrrev_i32_e32 v151, 31, v150
	v_mul_lo_u32 v162, s35, v154
	v_mul_lo_u32 v163, s34, v155
	s_cbranch_vccnz .LBB0_506
	v_mad_u64_u32 v[152:153], s[52:53], s34, v154, 0
	v_add3_u32 v153, v153, v163, v162
	v_lshl_add_u64 v[152:153], v[152:153], 1, s[30:31]
	v_lshl_add_u64 v[152:153], v[150:151], 1, v[152:153]
	s_mov_b64 s[68:69], 0
	v_cvt_pk_bf16_f32 v158, v130, v131
	v_cvt_pk_bf16_f32 v159, v132, v133
	v_cvt_pk_bf16_f32 v160, v134, v135
	v_cvt_pk_bf16_f32 v161, v136, v137
	global_store_dwordx4 v[152:153], v[158:161], off
.LBB0_506:
	s_ashr_i32 s52, s36, 2
	s_ashr_i32 s53, s52, 31
	s_lshl_b64 s[60:61], s[52:53], 20
	s_lshl_b32 s6, s52, 21
	s_ashr_i32 s52, s36, 3
	s_ashr_i32 s53, s52, 31
	v_and_b32_e32 v152, 0x378, v150
	s_and_b32 s49, s6, 0x200000
	s_lshl_b64 s[58:59], s[52:53], 21
	v_lshlrev_b64 v[160:161], 11, v[154:155]
	v_lshlrev_b64 v[158:159], 12, v[154:155]
	s_andn2_b64 vcc, exec, s[68:69]
	v_lshlrev_b32_e32 v0, 1, v152
	v_lshlrev_b32_e32 v152, 2, v152
	s_cbranch_vccnz .LBB0_508
	s_add_u32 s52, s30, s60
	s_addc_u32 s53, s31, s61
	s_lshl_b32 s6, s49, 2
	s_add_u32 s6, s28, s6
	v_lshl_add_u64 v[164:165], s[52:53], 0, v[160:161]
	s_addc_u32 s53, s29, 0
	s_add_u32 s52, s6, s58
	v_lshl_add_u64 v[164:165], v[164:165], 0, v[0:1]
	s_addc_u32 s53, s53, s59
	v_cvt_pk_bf16_f32 v180, v130, v131
	v_cvt_pk_bf16_f32 v181, v132, v133
	v_cvt_pk_bf16_f32 v182, v134, v135
	v_cvt_pk_bf16_f32 v183, v136, v137
	global_store_dwordx4 v[164:165], v[180:183], off
	v_lshl_add_u64 v[164:165], s[52:53], 0, v[158:159]
	v_mov_b32_e32 v153, v1
	v_lshl_add_u64 v[164:165], v[164:165], 0, v[152:153]
	global_store_dwordx4 v[164:165], v[130:133], off
	global_store_dwordx4 v[164:165], v[134:137], off offset:16
.LBB0_508:
	v_mov_b32_e32 v157, v156
	s_nop 0
	v_mov_b32_e32 v134, v156
	v_mov_b32_e32 v135, v156
	v_pk_mul_f32 v[132:133], v[64:65], v[134:135]
	v_pk_mul_f32 v[130:131], v[62:63], v[156:157]
	v_pk_mul_f32 v[136:137], v[60:61], v[134:135]
	v_pk_mul_f32 v[134:135], v[58:59], v[156:157]
	s_mov_b64 s[52:53], -1
	s_and_b64 vcc, exec, s[26:27]
	v_readlane_b32 s68, v255, 12
	s_cbranch_vccz .LBB0_510
	v_mad_u64_u32 v[154:155], s[52:53], s34, v154, 0
	v_add3_u32 v155, v155, v163, v162
	v_lshl_add_u64 v[154:155], v[154:155], 1, s[30:31]
	v_lshl_add_u64 v[154:155], v[150:151], 1, v[154:155]
	v_cvt_pk_bf16_f32 v180, v130, v131
	v_cvt_pk_bf16_f32 v181, v132, v133
	v_cvt_pk_bf16_f32 v182, v134, v135
	v_cvt_pk_bf16_f32 v183, v136, v137
	global_store_dwordx4 v[154:155], v[180:183], off offset:256
	s_mov_b64 s[52:53], 0
.LBB0_510:
	v_or_b32_e32 v153, 0x80, v150
	v_and_b32_e32 v153, 0x3f8, v153
	s_andn2_b64 vcc, exec, s[52:53]
	v_lshlrev_b32_e32 v156, 1, v153
	v_lshlrev_b32_e32 v154, 2, v153
	s_cbranch_vccnz .LBB0_512
	s_add_u32 s52, s30, s60
	s_addc_u32 s53, s31, s61
	s_lshl_b32 s6, s49, 2
	s_add_u32 s6, s28, s6
	v_lshl_add_u64 v[160:161], s[52:53], 0, v[160:161]
	s_addc_u32 s53, s29, 0
	s_add_u32 s52, s6, s58
	s_addc_u32 s53, s53, s59
	v_mov_b32_e32 v157, v1
	v_lshl_add_u64 v[158:159], s[52:53], 0, v[158:159]
	v_mov_b32_e32 v155, v1
	v_lshl_add_u64 v[160:161], v[160:161], 0, v[156:157]
	v_lshl_add_u64 v[158:159], v[158:159], 0, v[154:155]
	v_cvt_pk_bf16_f32 v162, v130, v131
	v_cvt_pk_bf16_f32 v163, v132, v133
	v_cvt_pk_bf16_f32 v164, v134, v135
	v_cvt_pk_bf16_f32 v165, v136, v137
	global_store_dwordx4 v[160:161], v[162:165], off
	global_store_dwordx4 v[158:159], v[130:133], off
	global_store_dwordx4 v[158:159], v[134:137], off offset:16
; #define LAS __attribute__((address_space(3)))
;     __device__ __forceinline__ void operator()(const f32x4 (&acc)[2][2][4][2], const Unit& u, const LAS float* rsl, int wr, int wc, int fr, int fq) const {
; #pragma unroll
;         for (int ai = 0; ai < 2; ++ai)
; #pragma unroll
;             for (int m = 0; m < 4; ++m) {
;                 const int rl = ai * HALF + wr * 64 + m * 16 + fr, row = u.pm * BM + rl;
;                 const float rs = rsl[rl] * cs;
; #pragma unroll
;                 for (int bj = 0; bj < 2; ++bj) {
;                     const int col = u.pn * BM + bj * HALF + wc * 32 + 8 * fq;
;                     const f32x4 v0 = acc[ai][bj][m][0] * rs, v1 = acc[ai][bj][m][1] * rs;
;                     if (mode == 0) {
;                         *(bf16x8*)(O + (size_t)row * ldc + col) = pack8v(v0, v1);
;                     } else {
;                         const int t = col >> 10, c = col & 1023;
;                         *(bf16x8*)(O + ((size_t)t * 512 + row) * 1024 + c) = pack8v(v0, v1);
;                         float* o = out32 + (size_t)(t & 1) * (OFF_MV - OFF_MK) + (size_t)(t >> 1) * (512 * 1024) + (size_t)row * 1024 + c;
;                         *(f32x4*)o = v0; *(f32x4*)(o + 4) = v1;
;                     }
;                 }
;             }
;     }
.LBB0_512:
	ds_read_b32 v130, v178 offset:64
	v_add_u32_e32 v158, s51, v168
	v_ashrrev_i32_e32 v159, 31, v158
	s_mov_b64 s[52:53], -1
	s_and_b64 vcc, exec, s[26:27]
	s_waitcnt lgkmcnt(0)
	v_mul_f32_e32 v164, s17, v130
	v_pk_mul_f32 v[132:133], v[88:89], v[164:165] op_sel_hi:[1,0]
	v_pk_mul_f32 v[130:131], v[86:87], v[164:165] op_sel_hi:[1,0]
	v_pk_mul_f32 v[136:137], v[84:85], v[164:165] op_sel_hi:[1,0]
	v_pk_mul_f32 v[134:135], v[82:83], v[164:165] op_sel_hi:[1,0]
	v_mul_lo_u32 v155, s35, v158
	v_mul_lo_u32 v157, s34, v159
	s_cbranch_vccz .LBB0_514
	v_mad_u64_u32 v[180:181], s[52:53], s34, v158, 0
	v_add3_u32 v181, v181, v157, v155
	v_lshl_add_u64 v[180:181], v[180:181], 1, s[30:31]
	v_lshl_add_u64 v[180:181], v[150:151], 1, v[180:181]
	v_cvt_pk_bf16_f32 v160, v130, v131
	v_cvt_pk_bf16_f32 v161, v132, v133
	v_cvt_pk_bf16_f32 v162, v134, v135
	v_cvt_pk_bf16_f32 v163, v136, v137
	global_store_dwordx4 v[180:181], v[160:163], off
	s_mov_b64 s[52:53], 0
.LBB0_514:
	s_nop 0
	v_lshlrev_b64 v[162:163], 11, v[158:159]
	s_andn2_b64 vcc, exec, s[52:53]
	v_lshlrev_b64 v[160:161], 12, v[158:159]
	s_cbranch_vccnz .LBB0_516
	s_add_u32 s52, s30, s60
	s_addc_u32 s53, s31, s61
	s_lshl_b32 s6, s49, 2
	s_add_u32 s6, s28, s6
	v_lshl_add_u64 v[184:185], s[52:53], 0, v[162:163]
	s_addc_u32 s53, s29, 0
	s_add_u32 s52, s6, s58
	v_cvt_pk_bf16_f32 v180, v130, v131
	v_cvt_pk_bf16_f32 v181, v132, v133
	v_lshl_add_u64 v[184:185], v[184:185], 0, v[0:1]
	s_addc_u32 s53, s53, s59
	v_cvt_pk_bf16_f32 v182, v134, v135
	v_cvt_pk_bf16_f32 v183, v136, v137
	global_store_dwordx4 v[184:185], v[180:183], off
	v_mov_b32_e32 v153, v1
	s_nop 0
	v_lshl_add_u64 v[180:181], s[52:53], 0, v[160:161]
	v_lshl_add_u64 v[180:181], v[180:181], 0, v[152:153]
	global_store_dwordx4 v[180:181], v[130:133], off
	global_store_dwordx4 v[180:181], v[134:137], off offset:16
.LBB0_516:
	v_mov_b32_e32 v165, v164
	s_nop 0
	v_mov_b32_e32 v134, v164
	v_mov_b32_e32 v135, v164
	v_pk_mul_f32 v[132:133], v[56:57], v[134:135]
	v_pk_mul_f32 v[130:131], v[54:55], v[164:165]
	v_pk_mul_f32 v[136:137], v[52:53], v[134:135]
	v_pk_mul_f32 v[134:135], v[50:51], v[164:165]
	s_mov_b64 s[52:53], -1
	s_and_b64 vcc, exec, s[26:27]
	s_cbranch_vccz .LBB0_518
	v_mad_u64_u32 v[158:159], s[52:53], s34, v158, 0
	v_add3_u32 v159, v159, v157, v155
	v_lshl_add_u64 v[158:159], v[158:159], 1, s[30:31]
	v_lshl_add_u64 v[158:159], v[150:151], 1, v[158:159]
	v_cvt_pk_bf16_f32 v180, v130, v131
	v_cvt_pk_bf16_f32 v181, v132, v133
	v_cvt_pk_bf16_f32 v182, v134, v135
	v_cvt_pk_bf16_f32 v183, v136, v137
	global_store_dwordx4 v[158:159], v[180:183], off offset:256
	s_mov_b64 s[52:53], 0
.LBB0_518:
	s_andn2_b64 vcc, exec, s[52:53]
	s_cbranch_vccnz .LBB0_520
	s_add_u32 s52, s30, s60
	s_addc_u32 s53, s31, s61
	s_lshl_b32 s6, s49, 2
	s_add_u32 s6, s28, s6
	v_lshl_add_u64 v[158:159], s[52:53], 0, v[162:163]
	s_addc_u32 s53, s29, 0
	v_mov_b32_e32 v157, v1
	s_add_u32 s52, s6, s58
	v_lshl_add_u64 v[158:159], v[158:159], 0, v[156:157]
	s_addc_u32 s53, s53, s59
	v_cvt_pk_bf16_f32 v180, v130, v131
	v_cvt_pk_bf16_f32 v181, v132, v133
	v_cvt_pk_bf16_f32 v182, v134, v135
	v_cvt_pk_bf16_f32 v183, v136, v137
	global_store_dwordx4 v[158:159], v[180:183], off
	v_lshl_add_u64 v[158:159], s[52:53], 0, v[160:161]
	v_mov_b32_e32 v155, v1
	v_lshl_add_u64 v[158:159], v[158:159], 0, v[154:155]
	global_store_dwordx4 v[158:159], v[130:133], off
	global_store_dwordx4 v[158:159], v[134:137], off offset:16
.LBB0_520:
	ds_read_b32 v130, v178 offset:128
	v_add_u32_e32 v158, s51, v169
	v_ashrrev_i32_e32 v159, 31, v158
	s_mov_b64 s[52:53], -1
	s_and_b64 vcc, exec, s[26:27]
	s_waitcnt lgkmcnt(0)
	v_mul_f32_e32 v164, s17, v130
	v_pk_mul_f32 v[132:133], v[80:81], v[164:165] op_sel_hi:[1,0]
	v_pk_mul_f32 v[130:131], v[78:79], v[164:165] op_sel_hi:[1,0]
	v_pk_mul_f32 v[136:137], v[76:77], v[164:165] op_sel_hi:[1,0]
	v_pk_mul_f32 v[134:135], v[74:75], v[164:165] op_sel_hi:[1,0]
	v_mul_lo_u32 v155, s35, v158
	v_mul_lo_u32 v157, s34, v159
	s_cbranch_vccz .LBB0_522
	v_mad_u64_u32 v[180:181], s[52:53], s34, v158, 0
	v_add3_u32 v181, v181, v157, v155
	v_lshl_add_u64 v[180:181], v[180:181], 1, s[30:31]
	v_lshl_add_u64 v[180:181], v[150:151], 1, v[180:181]
	v_cvt_pk_bf16_f32 v160, v130, v131
	v_cvt_pk_bf16_f32 v161, v132, v133
	v_cvt_pk_bf16_f32 v162, v134, v135
	v_cvt_pk_bf16_f32 v163, v136, v137
	global_store_dwordx4 v[180:181], v[160:163], off
	s_mov_b64 s[52:53], 0

;     __device__ __forceinline__ void operator()(const f32x4 (&acc)[2][2][4][2], const Unit& u, const LAS float* rsl, int wr, int wc, int fr, int fq) const {
;     ...
;                 const float rs = rsl[rl] * cs;
; #pragma unroll
;                 for (int bj = 0; bj < 2; ++bj) {
;                     const int col = u.pn * BM + bj * HALF + wc * 32 + 8 * fq;
;                     const f32x4 v0 = acc[ai][bj][m][0] * rs, v1 = acc[ai][bj][m][1] * rs;
;                     if (mode == 0) {
;                         *(bf16x8*)(O + (size_t)row * ldc + col) = pack8v(v0, v1);
.LBB0_524:
	v_mov_b32_e32 v165, v164
	s_nop 0
	v_mov_b32_e32 v134, v164
	v_mov_b32_e32 v135, v164
	v_pk_mul_f32 v[132:133], v[48:49], v[134:135]
	v_pk_mul_f32 v[130:131], v[46:47], v[164:165]
	v_pk_mul_f32 v[136:137], v[44:45], v[134:135]
	v_pk_mul_f32 v[134:135], v[42:43], v[164:165]
	s_mov_b64 s[52:53], -1
	s_and_b64 vcc, exec, s[26:27]
	s_cbranch_vccz .LBB0_526
	v_mad_u64_u32 v[158:159], s[52:53], s34, v158, 0
	v_add3_u32 v159, v159, v157, v155
	v_lshl_add_u64 v[158:159], v[158:159], 1, s[30:31]
	v_lshl_add_u64 v[158:159], v[150:151], 1, v[158:159]
	v_cvt_pk_bf16_f32 v180, v130, v131
	v_cvt_pk_bf16_f32 v181, v132, v133
	v_cvt_pk_bf16_f32 v182, v134, v135
	v_cvt_pk_bf16_f32 v183, v136, v137
	global_store_dwordx4 v[158:159], v[180:183], off offset:256
	s_mov_b64 s[52:53], 0

;     __device__ __forceinline__ void operator()(const f32x4 (&acc)[2][2][4][2], const Unit& u, const LAS float* rsl, int wr, int wc, int fr, int fq) const {
;     ...
;                 const int rl = ai * HALF + wr * 64 + m * 16 + fr, row = u.pm * BM + rl;
;                 const float rs = rsl[rl] * cs;
; #pragma unroll
;                 for (int bj = 0; bj < 2; ++bj) {
;                     const int col = u.pn * BM + bj * HALF + wc * 32 + 8 * fq;
;                     const f32x4 v0 = acc[ai][bj][m][0] * rs, v1 = acc[ai][bj][m][1] * rs;
;                     if (mode == 0) {
;                         *(bf16x8*)(O + (size_t)row * ldc + col) = pack8v(v0, v1);
.LBB0_528:
	ds_read_b32 v130, v178 offset:192
	v_add_u32_e32 v158, s51, v170
	v_ashrrev_i32_e32 v159, 31, v158
	s_mov_b64 s[52:53], -1
	s_and_b64 vcc, exec, s[26:27]
	s_waitcnt lgkmcnt(0)
	v_mul_f32_e32 v164, s17, v130
	v_pk_mul_f32 v[132:133], v[72:73], v[164:165] op_sel_hi:[1,0]
	v_pk_mul_f32 v[130:131], v[70:71], v[164:165] op_sel_hi:[1,0]
	v_pk_mul_f32 v[136:137], v[68:69], v[164:165] op_sel_hi:[1,0]
	v_pk_mul_f32 v[134:135], v[66:67], v[164:165] op_sel_hi:[1,0]
	v_mul_lo_u32 v155, s35, v158
	v_mul_lo_u32 v157, s34, v159
	s_cbranch_vccz .LBB0_530
	v_mad_u64_u32 v[180:181], s[52:53], s34, v158, 0
	v_add3_u32 v181, v181, v157, v155
	v_lshl_add_u64 v[180:181], v[180:181], 1, s[30:31]
	v_lshl_add_u64 v[180:181], v[150:151], 1, v[180:181]
	v_cvt_pk_bf16_f32 v160, v130, v131
	v_cvt_pk_bf16_f32 v161, v132, v133
	v_cvt_pk_bf16_f32 v162, v134, v135
	v_cvt_pk_bf16_f32 v163, v136, v137
	global_store_dwordx4 v[180:181], v[160:163], off
	s_mov_b64 s[52:53], 0

;     __device__ __forceinline__ void operator()(const f32x4 (&acc)[2][2][4][2], const Unit& u, const LAS float* rsl, int wr, int wc, int fr, int fq) const {
;     ...
;                 const float rs = rsl[rl] * cs;
; #pragma unroll
;                 for (int bj = 0; bj < 2; ++bj) {
;                     const int col = u.pn * BM + bj * HALF + wc * 32 + 8 * fq;
;                     const f32x4 v0 = acc[ai][bj][m][0] * rs, v1 = acc[ai][bj][m][1] * rs;
;                     if (mode == 0) {
;                         *(bf16x8*)(O + (size_t)row * ldc + col) = pack8v(v0, v1);
.LBB0_532:
	v_mov_b32_e32 v165, v164
	s_nop 0
	v_mov_b32_e32 v134, v164
	v_mov_b32_e32 v135, v164
	v_pk_mul_f32 v[132:133], v[40:41], v[134:135]
	v_pk_mul_f32 v[130:131], v[38:39], v[164:165]
	v_pk_mul_f32 v[136:137], v[36:37], v[134:135]
	v_pk_mul_f32 v[134:135], v[34:35], v[164:165]
	s_mov_b64 s[52:53], -1
	s_and_b64 vcc, exec, s[26:27]
	s_cbranch_vccz .LBB0_534
	v_mad_u64_u32 v[158:159], s[52:53], s34, v158, 0
	v_add3_u32 v159, v159, v157, v155
	v_lshl_add_u64 v[158:159], v[158:159], 1, s[30:31]
	v_lshl_add_u64 v[158:159], v[150:151], 1, v[158:159]
	v_cvt_pk_bf16_f32 v180, v130, v131
	v_cvt_pk_bf16_f32 v181, v132, v133
	v_cvt_pk_bf16_f32 v182, v134, v135
	v_cvt_pk_bf16_f32 v183, v136, v137
	global_store_dwordx4 v[158:159], v[180:183], off offset:256
	s_mov_b64 s[52:53], 0

;     __device__ __forceinline__ void operator()(const f32x4 (&acc)[2][2][4][2], const Unit& u, const LAS float* rsl, int wr, int wc, int fr, int fq) const {
;     ...
;                 const int rl = ai * HALF + wr * 64 + m * 16 + fr, row = u.pm * BM + rl;
;                 const float rs = rsl[rl] * cs;
; #pragma unroll
;                 for (int bj = 0; bj < 2; ++bj) {
;                     const int col = u.pn * BM + bj * HALF + wc * 32 + 8 * fq;
;                     const f32x4 v0 = acc[ai][bj][m][0] * rs, v1 = acc[ai][bj][m][1] * rs;
;                     if (mode == 0) {
;                         *(bf16x8*)(O + (size_t)row * ldc + col) = pack8v(v0, v1);
.LBB0_536:
	ds_read_b32 v130, v178 offset:512
	v_add_u32_e32 v158, s51, v171
	v_ashrrev_i32_e32 v159, 31, v158
	s_mov_b64 s[52:53], -1
	s_and_b64 vcc, exec, s[26:27]
	s_waitcnt lgkmcnt(0)
	v_mul_f32_e32 v164, s17, v130
	v_pk_mul_f32 v[132:133], v[32:33], v[164:165] op_sel_hi:[1,0]
	v_pk_mul_f32 v[130:131], v[30:31], v[164:165] op_sel_hi:[1,0]
	v_pk_mul_f32 v[136:137], v[28:29], v[164:165] op_sel_hi:[1,0]
	v_pk_mul_f32 v[134:135], v[26:27], v[164:165] op_sel_hi:[1,0]
	v_mul_lo_u32 v155, s35, v158
	v_mul_lo_u32 v157, s34, v159
	s_cbranch_vccz .LBB0_538
	v_mad_u64_u32 v[180:181], s[52:53], s34, v158, 0
	v_add3_u32 v181, v181, v157, v155
	v_lshl_add_u64 v[180:181], v[180:181], 1, s[30:31]
	v_lshl_add_u64 v[180:181], v[150:151], 1, v[180:181]
	v_cvt_pk_bf16_f32 v160, v130, v131
	v_cvt_pk_bf16_f32 v161, v132, v133
	v_cvt_pk_bf16_f32 v162, v134, v135
	v_cvt_pk_bf16_f32 v163, v136, v137
	global_store_dwordx4 v[180:181], v[160:163], off
	s_mov_b64 s[52:53], 0

;     __device__ __forceinline__ void operator()(const f32x4 (&acc)[2][2][4][2], const Unit& u, const LAS float* rsl, int wr, int wc, int fr, int fq) const {
;     ...
;                 const float rs = rsl[rl] * cs;
; #pragma unroll
;                 for (int bj = 0; bj < 2; ++bj) {
;                     const int col = u.pn * BM + bj * HALF + wc * 32 + 8 * fq;
;                     const f32x4 v0 = acc[ai][bj][m][0] * rs, v1 = acc[ai][bj][m][1] * rs;
;                     if (mode == 0) {
;                         *(bf16x8*)(O + (size_t)row * ldc + col) = pack8v(v0, v1);
.LBB0_540:
	v_mov_b32_e32 v165, v164
	s_nop 0
	v_mov_b32_e32 v134, v164
	v_mov_b32_e32 v135, v164
	v_pk_mul_f32 v[132:133], v[100:101], v[134:135]
	v_pk_mul_f32 v[130:131], v[98:99], v[164:165]
	v_pk_mul_f32 v[136:137], v[104:105], v[134:135]
	v_pk_mul_f32 v[134:135], v[102:103], v[164:165]
	s_mov_b64 s[52:53], -1
	s_and_b64 vcc, exec, s[26:27]
	s_cbranch_vccz .LBB0_542
	v_mad_u64_u32 v[158:159], s[52:53], s34, v158, 0
	v_add3_u32 v159, v159, v157, v155
	v_lshl_add_u64 v[158:159], v[158:159], 1, s[30:31]
	v_lshl_add_u64 v[158:159], v[150:151], 1, v[158:159]
	v_cvt_pk_bf16_f32 v180, v130, v131
	v_cvt_pk_bf16_f32 v181, v132, v133
	v_cvt_pk_bf16_f32 v182, v134, v135
	v_cvt_pk_bf16_f32 v183, v136, v137
	global_store_dwordx4 v[158:159], v[180:183], off offset:256
	s_mov_b64 s[52:53], 0

;     __device__ __forceinline__ void operator()(const f32x4 (&acc)[2][2][4][2], const Unit& u, const LAS float* rsl, int wr, int wc, int fr, int fq) const {
;     ...
;                 const int rl = ai * HALF + wr * 64 + m * 16 + fr, row = u.pm * BM + rl;
;                 const float rs = rsl[rl] * cs;
; #pragma unroll
;                 for (int bj = 0; bj < 2; ++bj) {
;                     const int col = u.pn * BM + bj * HALF + wc * 32 + 8 * fq;
;                     const f32x4 v0 = acc[ai][bj][m][0] * rs, v1 = acc[ai][bj][m][1] * rs;
;                     if (mode == 0) {
;                         *(bf16x8*)(O + (size_t)row * ldc + col) = pack8v(v0, v1);
.LBB0_544:
	ds_read_b32 v130, v178 offset:576
	v_add_u32_e32 v158, s51, v172
	v_ashrrev_i32_e32 v159, 31, v158
	s_mov_b64 s[52:53], -1
	s_and_b64 vcc, exec, s[26:27]
	s_waitcnt lgkmcnt(0)
	v_mul_f32_e32 v164, s17, v130
	v_pk_mul_f32 v[132:133], v[24:25], v[164:165] op_sel_hi:[1,0]
	v_pk_mul_f32 v[130:131], v[22:23], v[164:165] op_sel_hi:[1,0]
	v_pk_mul_f32 v[136:137], v[20:21], v[164:165] op_sel_hi:[1,0]
	v_pk_mul_f32 v[134:135], v[18:19], v[164:165] op_sel_hi:[1,0]
	v_mul_lo_u32 v155, s35, v158
	v_mul_lo_u32 v157, s34, v159
	s_cbranch_vccz .LBB0_546
	v_mad_u64_u32 v[180:181], s[52:53], s34, v158, 0
	v_add3_u32 v181, v181, v157, v155
	v_lshl_add_u64 v[180:181], v[180:181], 1, s[30:31]
	v_lshl_add_u64 v[180:181], v[150:151], 1, v[180:181]
	v_cvt_pk_bf16_f32 v160, v130, v131
	v_cvt_pk_bf16_f32 v161, v132, v133
	v_cvt_pk_bf16_f32 v162, v134, v135
	v_cvt_pk_bf16_f32 v163, v136, v137
	global_store_dwordx4 v[180:181], v[160:163], off
	s_mov_b64 s[52:53], 0

;     __device__ __forceinline__ void operator()(const f32x4 (&acc)[2][2][4][2], const Unit& u, const LAS float* rsl, int wr, int wc, int fr, int fq) const {
;     ...
;                 const float rs = rsl[rl] * cs;
; #pragma unroll
;                 for (int bj = 0; bj < 2; ++bj) {
;                     const int col = u.pn * BM + bj * HALF + wc * 32 + 8 * fq;
;                     const f32x4 v0 = acc[ai][bj][m][0] * rs, v1 = acc[ai][bj][m][1] * rs;
;                     if (mode == 0) {
;                         *(bf16x8*)(O + (size_t)row * ldc + col) = pack8v(v0, v1);
.LBB0_548:
	v_mov_b32_e32 v165, v164
	s_nop 0
	v_mov_b32_e32 v134, v164
	v_mov_b32_e32 v135, v164
	v_pk_mul_f32 v[132:133], v[108:109], v[134:135]
	v_pk_mul_f32 v[130:131], v[106:107], v[164:165]
	v_pk_mul_f32 v[136:137], v[112:113], v[134:135]
	v_pk_mul_f32 v[134:135], v[110:111], v[164:165]
	s_mov_b64 s[52:53], -1
	s_and_b64 vcc, exec, s[26:27]
	s_cbranch_vccz .LBB0_550
	v_mad_u64_u32 v[158:159], s[52:53], s34, v158, 0
	v_add3_u32 v159, v159, v157, v155
	v_lshl_add_u64 v[158:159], v[158:159], 1, s[30:31]
	v_lshl_add_u64 v[158:159], v[150:151], 1, v[158:159]
	v_cvt_pk_bf16_f32 v180, v130, v131
	v_cvt_pk_bf16_f32 v181, v132, v133
	v_cvt_pk_bf16_f32 v182, v134, v135
	v_cvt_pk_bf16_f32 v183, v136, v137
	global_store_dwordx4 v[158:159], v[180:183], off offset:256
	s_mov_b64 s[52:53], 0

;     __device__ __forceinline__ void operator()(const f32x4 (&acc)[2][2][4][2], const Unit& u, const LAS float* rsl, int wr, int wc, int fr, int fq) const {
;     ...
;                 const int rl = ai * HALF + wr * 64 + m * 16 + fr, row = u.pm * BM + rl;
;                 const float rs = rsl[rl] * cs;
; #pragma unroll
;                 for (int bj = 0; bj < 2; ++bj) {
;                     const int col = u.pn * BM + bj * HALF + wc * 32 + 8 * fq;
;                     const f32x4 v0 = acc[ai][bj][m][0] * rs, v1 = acc[ai][bj][m][1] * rs;
;                     if (mode == 0) {
;                         *(bf16x8*)(O + (size_t)row * ldc + col) = pack8v(v0, v1);
.LBB0_552:
	ds_read_b32 v130, v178 offset:640
	v_add_u32_e32 v158, s51, v173
	v_ashrrev_i32_e32 v159, 31, v158
	s_mov_b64 s[52:53], -1
	s_and_b64 vcc, exec, s[26:27]
	s_waitcnt lgkmcnt(0)
	v_mul_f32_e32 v164, s17, v130
	v_pk_mul_f32 v[132:133], v[16:17], v[164:165] op_sel_hi:[1,0]
	v_pk_mul_f32 v[130:131], v[14:15], v[164:165] op_sel_hi:[1,0]
	v_pk_mul_f32 v[136:137], v[12:13], v[164:165] op_sel_hi:[1,0]
	v_pk_mul_f32 v[134:135], v[10:11], v[164:165] op_sel_hi:[1,0]
	v_mul_lo_u32 v155, s35, v158
	v_mul_lo_u32 v157, s34, v159
	s_cbranch_vccz .LBB0_554
	v_mad_u64_u32 v[180:181], s[52:53], s34, v158, 0
	v_add3_u32 v181, v181, v157, v155
	v_lshl_add_u64 v[180:181], v[180:181], 1, s[30:31]
	v_lshl_add_u64 v[180:181], v[150:151], 1, v[180:181]
	v_cvt_pk_bf16_f32 v160, v130, v131
	v_cvt_pk_bf16_f32 v161, v132, v133
	v_cvt_pk_bf16_f32 v162, v134, v135
	v_cvt_pk_bf16_f32 v163, v136, v137
	global_store_dwordx4 v[180:181], v[160:163], off
	s_mov_b64 s[52:53], 0

;     __device__ __forceinline__ void operator()(const f32x4 (&acc)[2][2][4][2], const Unit& u, const LAS float* rsl, int wr, int wc, int fr, int fq) const {
;     ...
;                 const float rs = rsl[rl] * cs;
; #pragma unroll
;                 for (int bj = 0; bj < 2; ++bj) {
;                     const int col = u.pn * BM + bj * HALF + wc * 32 + 8 * fq;
;                     const f32x4 v0 = acc[ai][bj][m][0] * rs, v1 = acc[ai][bj][m][1] * rs;
;                     if (mode == 0) {
;                         *(bf16x8*)(O + (size_t)row * ldc + col) = pack8v(v0, v1);
.LBB0_556:
	v_mov_b32_e32 v165, v164
	s_nop 0
	v_mov_b32_e32 v134, v164
	v_mov_b32_e32 v135, v164
	v_pk_mul_f32 v[132:133], v[116:117], v[134:135]
	v_pk_mul_f32 v[130:131], v[114:115], v[164:165]
	v_pk_mul_f32 v[136:137], v[120:121], v[134:135]
	v_pk_mul_f32 v[134:135], v[118:119], v[164:165]
	s_mov_b64 s[52:53], -1
	s_and_b64 vcc, exec, s[26:27]
	s_cbranch_vccz .LBB0_558
	v_mad_u64_u32 v[158:159], s[52:53], s34, v158, 0
	v_add3_u32 v159, v159, v157, v155
	v_lshl_add_u64 v[158:159], v[158:159], 1, s[30:31]
	v_lshl_add_u64 v[158:159], v[150:151], 1, v[158:159]
	v_cvt_pk_bf16_f32 v180, v130, v131
	v_cvt_pk_bf16_f32 v181, v132, v133
	v_cvt_pk_bf16_f32 v182, v134, v135
	v_cvt_pk_bf16_f32 v183, v136, v137
	global_store_dwordx4 v[158:159], v[180:183], off offset:256
	s_mov_b64 s[52:53], 0

;     __device__ __forceinline__ void operator()(const f32x4 (&acc)[2][2][4][2], const Unit& u, const LAS float* rsl, int wr, int wc, int fr, int fq) const {
;     ...
;                 const int rl = ai * HALF + wr * 64 + m * 16 + fr, row = u.pm * BM + rl;
;                 const float rs = rsl[rl] * cs;
; #pragma unroll
;                 for (int bj = 0; bj < 2; ++bj) {
;                     const int col = u.pn * BM + bj * HALF + wc * 32 + 8 * fq;
;                     const f32x4 v0 = acc[ai][bj][m][0] * rs, v1 = acc[ai][bj][m][1] * rs;
;                     if (mode == 0) {
;                         *(bf16x8*)(O + (size_t)row * ldc + col) = pack8v(v0, v1);
;                     } else {
;                         const int t = col >> 10, c = col & 1023;
;                         *(bf16x8*)(O + ((size_t)t * 512 + row) * 1024 + c) = pack8v(v0, v1);
;                         float* o = out32 + (size_t)(t & 1) * (OFF_MV - OFF_MK) + (size_t)(t >> 1) * (512 * 1024) + (size_t)row * 1024 + c;
;                         *(f32x4*)o = v0; *(f32x4*)(o + 4) = v1;
;                     }
.LBB0_560:
	ds_read_b32 v130, v178 offset:704
	v_add_u32_e32 v158, s51, v174
	v_ashrrev_i32_e32 v159, 31, v158
	s_mov_b64 s[52:53], -1
	s_and_b64 vcc, exec, s[26:27]
	s_waitcnt lgkmcnt(0)
	v_mul_f32_e32 v164, s17, v130
	v_pk_mul_f32 v[132:133], v[8:9], v[164:165] op_sel_hi:[1,0]
	v_pk_mul_f32 v[130:131], v[6:7], v[164:165] op_sel_hi:[1,0]
	v_pk_mul_f32 v[136:137], v[4:5], v[164:165] op_sel_hi:[1,0]
	v_pk_mul_f32 v[134:135], v[2:3], v[164:165] op_sel_hi:[1,0]
	v_mul_lo_u32 v155, s35, v158
	v_mul_lo_u32 v157, s34, v159
	s_cbranch_vccz .LBB0_562
	v_mad_u64_u32 v[178:179], s[52:53], s34, v158, 0
	v_add3_u32 v179, v179, v157, v155
	v_lshl_add_u64 v[178:179], v[178:179], 1, s[30:31]
	v_lshl_add_u64 v[178:179], v[150:151], 1, v[178:179]
	v_cvt_pk_bf16_f32 v160, v130, v131
	v_cvt_pk_bf16_f32 v161, v132, v133
	v_cvt_pk_bf16_f32 v162, v134, v135
	v_cvt_pk_bf16_f32 v163, v136, v137
	global_store_dwordx4 v[178:179], v[160:163], off
	s_mov_b64 s[52:53], 0
.LBB0_562:
	s_nop 0
	v_lshlrev_b64 v[162:163], 11, v[158:159]
	s_andn2_b64 vcc, exec, s[52:53]
	v_lshlrev_b64 v[160:161], 12, v[158:159]
	s_cbranch_vccnz .LBB0_564
	s_add_u32 s52, s30, s60
	s_addc_u32 s53, s31, s61
	s_lshl_b32 s6, s49, 2
	s_add_u32 s6, s28, s6
	s_addc_u32 s51, s29, 0
	v_lshl_add_u64 v[182:183], s[52:53], 0, v[162:163]
	s_add_u32 s52, s6, s58
	v_cvt_pk_bf16_f32 v178, v130, v131
	v_cvt_pk_bf16_f32 v179, v132, v133
	v_lshl_add_u64 v[182:183], v[182:183], 0, v[0:1]
	s_addc_u32 s53, s51, s59
	v_cvt_pk_bf16_f32 v180, v134, v135
	v_cvt_pk_bf16_f32 v181, v136, v137
	global_store_dwordx4 v[182:183], v[178:181], off
	v_mov_b32_e32 v153, v1
	s_nop 0
	v_lshl_add_u64 v[178:179], s[52:53], 0, v[160:161]
	v_lshl_add_u64 v[152:153], v[178:179], 0, v[152:153]
	global_store_dwordx4 v[152:153], v[130:133], off
	global_store_dwordx4 v[152:153], v[134:137], off offset:16
.LBB0_564:
	v_mov_b32_e32 v165, v164
	s_nop 0
	v_mov_b32_e32 v134, v164
	v_mov_b32_e32 v135, v164
	v_pk_mul_f32 v[132:133], v[124:125], v[134:135]
	v_pk_mul_f32 v[130:131], v[122:123], v[164:165]
	v_pk_mul_f32 v[136:137], v[128:129], v[134:135]
	v_pk_mul_f32 v[134:135], v[126:127], v[164:165]
	s_mov_b64 s[52:53], -1
	s_and_b64 vcc, exec, s[26:27]
	s_cbranch_vccz .LBB0_569
	v_mad_u64_u32 v[152:153], s[52:53], s34, v158, 0
	v_add3_u32 v153, v153, v157, v155
	v_lshl_add_u64 v[152:153], v[152:153], 1, s[30:31]
	v_lshl_add_u64 v[150:151], v[150:151], 1, v[152:153]
	v_cvt_pk_bf16_f32 v178, v130, v131
	v_cvt_pk_bf16_f32 v179, v132, v133
	v_cvt_pk_bf16_f32 v180, v134, v135
	v_cvt_pk_bf16_f32 v181, v136, v137
	global_store_dwordx4 v[150:151], v[178:181], off offset:256
	s_cbranch_execz .LBB0_570

;     __device__ __forceinline__ void operator()(const f32x4 (&acc)[2][2][4][2], const Unit& u, const LAS float* rsl, int wr, int wc, int fr, int fq) const {
;     ...
;                     } else {
;                         const int t = col >> 10, c = col & 1023;
;                         *(bf16x8*)(O + ((size_t)t * 512 + row) * 1024 + c) = pack8v(v0, v1);
;                         float* o = out32 + (size_t)(t & 1) * (OFF_MV - OFF_MK) + (size_t)(t >> 1) * (512 * 1024) + (size_t)row * 1024 + c;
;                         *(f32x4*)o = v0; *(f32x4*)(o + 4) = v1;
;                     }
.LBB0_570:
	s_add_u32 s52, s30, s60
	s_addc_u32 s53, s31, s61
	s_lshl_b32 s6, s49, 2
	s_add_u32 s6, s28, s6
	s_addc_u32 s49, s29, 0
	v_lshl_add_u64 v[158:159], s[52:53], 0, v[162:163]
	v_mov_b32_e32 v157, v1
	s_add_u32 s52, s6, s58
	v_cvt_pk_bf16_f32 v150, v130, v131
	v_cvt_pk_bf16_f32 v151, v132, v133
	v_lshl_add_u64 v[156:157], v[158:159], 0, v[156:157]
	s_addc_u32 s53, s49, s59
	v_cvt_pk_bf16_f32 v152, v134, v135
	v_cvt_pk_bf16_f32 v153, v136, v137
	global_store_dwordx4 v[156:157], v[150:153], off
	v_mov_b32_e32 v155, v1
	s_nop 0
	v_lshl_add_u64 v[150:151], s[52:53], 0, v[160:161]
	v_lshl_add_u64 v[150:151], v[150:151], 0, v[154:155]
	global_store_dwordx4 v[150:151], v[130:133], off
	global_store_dwordx4 v[150:151], v[134:137], off offset:16
	s_add_u32 s52, s4, 0xffffff00
	s_addc_u32 s53, s5, -1
	s_andn2_b64 vcc, exec, s[2:3]
	s_cbranch_vccz .LBB0_567
